# p3: odd XCDs walk their item list backwards (h2 chunks first, gate tiles last)
# baseline (speedup 1.0000x reference)
; DEVI char* wsp(const Params& P, size_t off) { asm volatile("" : "+s"(off)); return P.ws + off; }
; DEVI int ltid() { int t = threadIdx.x; asm volatile("" : "+v"(t)); return t; }
; #define ZERO_ACC(a) _Pragma("unroll") for (int m_ = 0; m_ < 4; ++m_) _Pragma("unroll") for (int n_ = 0; n_ < 4; ++n_) a[m_][n_] = f32x4{0.f, 0.f, 0.f, 0.f}
; DEVI void gate_tile(const Params& P, int l, int pm, int q, char* smem, int tid) {
;   const int nb = q >> 1, hb = q & 1;
;   const bfu* cb = (const bfu*)wsp(P, O_CB);
;   const bfu* A = cb + (long)pm * 128 * 1024 + nb * 128;
;   const bfu* Wa = (const bfu*)wsp(P, O_LRU) + nb * 16384 + hb * 64 * 128;
;   const bfu* Wx = Wa + 8 * 16384;
;   float* au0 = (float*)wsp(P, O_AU);
;   float* au1 = au0 + (long)8448 * 1024;
;   const float* ba = P.in[12] + l * 1024;
;   const float* bx = P.in[14] + l * 1024;
;   const float* lam = P.in[15] + l * 1024;
;   f32x4 acc[4][4]; ZERO_ACC(acc);
;   gemm_core_t<1>(acc, A, 1024, Wa, 128, 128, smem, tid, Wx);
; DEVI void phase3(const Params& P, int l, int pass, char* smem) {
;   const int tid = ltid();
;   const int ntok = pass ? 8192 : 8448;
;   const int nG = (ntok / 128) * 16, nH2 = 1024;
;   for (int id = blockIdx.x; id < nG + nH2; id += gridDim.x) {
;     if (id < nG) gate_tile(P, l, id >> 4, id & 15, smem, tid);
;     else h2_item(P, l, pass, id - nG, tid);
;   }
; }
.LBB0_449:
	s_or_b64 exec, exec, s[26:27]
	s_barrier
	s_cmp_eq_u32 s90, 0
	s_movk_i32 s1, 0x420
	s_cselect_b32 s1, s1, 0x400
	s_add_i32 s2, s1, 0x400
	v_mov_b32_e32 v20, v93
	s_cmp_ge_i32 s74, s2
	s_cbranch_scc1 .LBB0_464
	v_lshlrev_b32_e32 v91, 4, v20
	v_ashrrev_i32_e32 v2, 3, v20
	v_xor_b32_e32 v4, v2, v20
	v_ashrrev_i32_e32 v3, 31, v2
	v_add_u32_e32 v102, 0x1000, v91
	v_lshlrev_b64 v[22:23], 10, v[2:3]
	v_lshlrev_b32_e32 v3, 3, v4
	v_ashrrev_i32_e32 v6, 7, v102
	v_and_b32_e32 v4, 56, v3
	v_xor_b32_e32 v3, v6, v20
	v_add_u32_e32 v103, 0x2000, v91
	v_lshlrev_b32_e32 v3, 3, v3
	v_ashrrev_i32_e32 v10, 7, v103
	v_and_b32_e32 v8, 56, v3
	v_xor_b32_e32 v3, v10, v20
	v_add_u32_e32 v104, 0x3000, v91
	v_lshlrev_b32_e32 v3, 3, v3
	v_ashrrev_i32_e32 v14, 7, v104
	v_and_b32_e32 v12, 56, v3
	v_xor_b32_e32 v3, v14, v20
	v_lshlrev_b32_e32 v3, 3, v3
	v_and_b32_e32 v16, 56, v3
	v_and_b32_e32 v3, 0x100, v20
	v_cmp_eq_u32_e64 s[40:41], 0, v3
	v_ashrrev_i32_e32 v3, 4, v20
	s_movk_i32 s4, 0xffe0
	v_bfi_b32 v2, s4, v3, v2
	v_ashrrev_i32_e32 v3, 31, v2
	v_lshlrev_b64 v[30:31], 8, v[2:3]
	v_ashrrev_i32_e32 v2, 8, v102
	v_bfi_b32 v2, s4, v2, v6
	v_ashrrev_i32_e32 v3, 31, v2
	v_lshlrev_b64 v[32:33], 8, v[2:3]
	v_ashrrev_i32_e32 v2, 8, v103
	v_bfi_b32 v2, s4, v2, v10
	v_ashrrev_i32_e32 v3, 31, v2
	v_lshlrev_b64 v[34:35], 8, v[2:3]
	v_and_b32_e32 v2, 0x1000, v104
	v_cmp_eq_u32_e64 s[42:43], 0, v2
	v_ashrrev_i32_e32 v2, 8, v104
	v_bfi_b32 v2, s4, v2, v14
	v_ashrrev_i32_e32 v3, 31, v2
	v_and_b32_e32 v5, 15, v20
	v_lshlrev_b64 v[36:37], 8, v[2:3]
	v_lshrrev_b32_e32 v2, 1, v20
	s_mov_b32 s4, 0x1ffffc0
	v_and_or_b32 v3, v2, s4, v5
	v_bfe_u32 v13, v20, 4, 2
	v_and_b32_e32 v5, 7, v20
	v_lshlrev_b32_e32 v106, 7, v3
	v_lshlrev_b32_e32 v3, 7, v20
	v_and_b32_e32 v107, 0x2780, v3
	v_bitop3_b32 v3, v13, v5, 4 bitop3:0x36
	s_lshl_b32 s26, s0, 10
	v_lshlrev_b32_e32 v108, 4, v3
	v_lshrrev_b32_e32 v3, 2, v20
	s_lshl_b32 s24, s0, 5
	s_lshl_b32 s56, s90, 4
	s_ashr_i32 s27, s26, 31
	v_and_b32_e32 v3, 12, v3
	s_mov_b32 s4, 0x7fffc0
	s_add_i32 s56, s56, s24
	v_and_or_b32 v2, v2, s4, v3
	s_lshl_b64 s[46:47], s[26:27], 2
	v_readlane_b32 s4, v252, 6
	v_readlane_b32 s5, v252, 7
	s_add_u32 s26, s4, s46
	v_lshrrev_b32_e32 v9, 4, v20
	v_ashrrev_i32_e32 v7, 31, v6
	v_and_b32_e32 v3, 0x4f, v20
	v_lshlrev_b32_e32 v2, 9, v2
	s_addc_u32 s27, s5, s47
	v_readlane_b32 s48, v253, 6
	v_lshlrev_b64 v[24:25], 10, v[6:7]
	v_bitop3_b32 v6, v9, v5, 3 bitop3:0x6c
	v_lshl_or_b32 v109, v3, 2, v2
	v_lshlrev_b32_e32 v2, 2, v20
	v_and_b32_e32 v5, 31, v20
	v_readlane_b32 s49, v253, 7
	s_add_u32 s48, s48, s46
	v_and_b32_e32 v110, 60, v2
	v_lshlrev_b32_e32 v2, 3, v20
	v_lshlrev_b32_e32 v5, 2, v5
	s_movk_i32 s24, 0xff00
	v_readlane_b32 s50, v253, 8
	s_addc_u32 s49, s49, s47
	v_and_b32_e32 v1, 0x7f, v20
	v_lshlrev_b32_e32 v3, 5, v20
	v_and_or_b32 v111, v2, s24, v5
	v_readlane_b32 s51, v253, 9
	s_add_u32 s50, s50, s46
	v_and_b32_e32 v2, 0x70, v91
	s_movk_i32 s24, 0x100
	v_lshlrev_b32_e32 v0, 7, v1
	v_ashrrev_i32_e32 v11, 31, v10
	v_ashrrev_i32_e32 v15, 31, v14
	s_addc_u32 s51, s51, s47
	v_and_or_b32 v112, v3, s24, v2
	s_lshl_b32 s24, s1, 8
	v_readlane_b32 s4, v252, 16
	v_lshlrev_b64 v[26:27], 10, v[10:11]
	v_lshlrev_b64 v[28:29], 10, v[14:15]
	v_lshlrev_b32_e32 v105, 4, v6
	v_cmp_gt_i32_e64 s[44:45], 64, v20
	v_ashrrev_i32_e32 v21, 31, v20
	s_sub_i32 s57, s74, s1
	s_sub_i32 s58, s4, s24
	v_lshlrev_b32_e32 v38, 2, v1
	v_mov_b32_e32 v39, v89
	v_lshlrev_b32_e32 v40, 2, v0
	v_lshlrev_b32_e32 v88, 1, v4
	v_lshlrev_b32_e32 v42, 1, v8
	v_lshlrev_b32_e32 v44, 1, v12
	v_lshlrev_b32_e32 v46, 1, v16
	s_mov_b32 s59, s74
	v_readlane_b32 s52, v253, 10
	v_readlane_b32 s53, v253, 11
	v_readlane_b32 s54, v253, 12
	v_readlane_b32 s55, v253, 13
	s_getreg_b32 vcc_lo, hwreg(HW_REG_XCC_ID, 0, 4)
	s_nop 1
	s_bitcmp1_b32 vcc_lo, 0
	s_cbranch_scc0 .LBB0_453
.Lp3_rev_init:
	s_add_i32 vcc_lo, s59, s23
	s_cmp_lt_i32 vcc_lo, s2
	s_cbranch_scc0 .LBB0_453
	s_mov_b32 s59, vcc_lo
	v_readlane_b32 vcc_hi, v252, 17
	s_add_i32 s57, s57, s23
	s_nop 2
	s_add_i32 s58, s58, vcc_hi
	s_branch .Lp3_rev_init

; DEVI void phase3(const Params& P, int l, int pass, char* smem) {
;     ...
;   for (int id = blockIdx.x; id < nG + nH2; id += gridDim.x) {
;     if (id < nG) gate_tile(P, l, id >> 4, id & 15, smem, tid);
;     else h2_item(P, l, pass, id - nG, tid);
.LBB0_452:
	v_readlane_b32 s4, v252, 17
	s_getreg_b32 vcc_lo, hwreg(HW_REG_XCC_ID, 0, 4)
	s_nop 1
	s_bitcmp1_b32 vcc_lo, 0
	s_cbranch_scc1 .Lp3_back
	s_add_i32 s59, s59, s23
	s_add_i32 s57, s57, s23
	s_add_i32 s58, s58, s4
	s_cmp_lt_i32 s59, s2
	s_cbranch_scc0 .LBB0_464
	s_branch .LBB0_453
.Lp3_back:
	s_sub_i32 s59, s59, s23
	s_sub_i32 s57, s57, s23
	s_sub_i32 s58, s58, s4
	s_cmp_ge_i32 s59, 0
	s_cbranch_scc0 .LBB0_464
